# v45 with the s_nop after each exp group removed (next instruction does not consume the last exp); scalar adds kept
# speedup vs baseline: 1.0070x; 1.0070x over previous
.Latt_noload:
	ds_read_b128 v[66:69], v0 offset:0
	ds_read_b128 v[70:73], v0 offset:6656
	ds_read_b128 v[74:77], v0 offset:32
	ds_read_b128 v[78:81], v0 offset:6688
	ds_read_b128 v[212:215], v0 offset:64
	ds_read_b128 v[240:243], v0 offset:6720
	ds_read_b128 v[244:247], v0 offset:96
	s_waitcnt lgkmcnt(6)
	v_mfma_f32_32x32x16_bf16 v[114:129], v[66:69], v[154:157], v[82:97]
	ds_read_b128 v[248:251], v0 offset:6752
	s_waitcnt lgkmcnt(6)
	v_mfma_f32_32x32x16_bf16 v[98:113], v[70:73], v[154:157], v[82:97]
	ds_read_b128 v[66:69], v0 offset:128
	s_waitcnt lgkmcnt(6)
	v_mfma_f32_32x32x16_bf16 v[114:129], v[74:77], v[158:161], v[114:129]
	ds_read_b128 v[70:73], v0 offset:6784
	s_waitcnt lgkmcnt(6)
	v_mfma_f32_32x32x16_bf16 v[98:113], v[78:81], v[158:161], v[98:113]
	ds_read_b128 v[74:77], v0 offset:160
	s_waitcnt lgkmcnt(6)
	v_mfma_f32_32x32x16_bf16 v[114:129], v[212:215], v[162:165], v[114:129]
	ds_read_b128 v[78:81], v0 offset:6816
	s_waitcnt lgkmcnt(6)
	v_mfma_f32_32x32x16_bf16 v[98:113], v[240:243], v[162:165], v[98:113]
	ds_read_b128 v[212:215], v0 offset:13312
	s_waitcnt lgkmcnt(6)
	v_mfma_f32_32x32x16_bf16 v[114:129], v[244:247], v[166:169], v[114:129]
	ds_read_b128 v[240:243], v0 offset:19968
	s_waitcnt lgkmcnt(6)
	v_mfma_f32_32x32x16_bf16 v[98:113], v[248:251], v[166:169], v[98:113]
	ds_read_b128 v[244:247], v0 offset:13344
	s_waitcnt lgkmcnt(6)
	v_mfma_f32_32x32x16_bf16 v[114:129], v[66:69], v[170:173], v[114:129]
	ds_read_b128 v[248:251], v0 offset:20000
	s_waitcnt lgkmcnt(6)
	v_mfma_f32_32x32x16_bf16 v[98:113], v[70:73], v[170:173], v[98:113]
	ds_read_b128 v[66:69], v0 offset:13376
	s_waitcnt lgkmcnt(6)
	v_mfma_f32_32x32x16_bf16 v[114:129], v[74:77], v[174:177], v[114:129]
	ds_read_b128 v[70:73], v0 offset:20032
	s_waitcnt lgkmcnt(6)
	v_mfma_f32_32x32x16_bf16 v[98:113], v[78:81], v[174:177], v[98:113]
	ds_read_b128 v[74:77], v0 offset:13408
	s_waitcnt lgkmcnt(6)
	v_mfma_f32_32x32x16_bf16 v[2:17], v[212:215], v[154:157], v[82:97]
	ds_read_b128 v[78:81], v0 offset:20064
	s_waitcnt lgkmcnt(6)
	v_mfma_f32_32x32x16_bf16 v[18:33], v[240:243], v[154:157], v[82:97]
	ds_read_b128 v[212:215], v0 offset:13440
	s_waitcnt lgkmcnt(6)
	v_mfma_f32_32x32x16_bf16 v[2:17], v[244:247], v[158:161], v[2:17]
	ds_read_b128 v[240:243], v0 offset:20096
	s_waitcnt lgkmcnt(6)
	v_mfma_f32_32x32x16_bf16 v[18:33], v[248:251], v[158:161], v[18:33]
	ds_read_b128 v[244:247], v0 offset:13472
	s_waitcnt lgkmcnt(6)
	v_mfma_f32_32x32x16_bf16 v[2:17], v[66:69], v[162:165], v[2:17]
	ds_read_b128 v[248:251], v0 offset:20128
	s_waitcnt lgkmcnt(6)
	v_mfma_f32_32x32x16_bf16 v[18:33], v[70:73], v[162:165], v[18:33]
	ds_read_b64_tr_b16 v[216:217], v185 offset:53248
	ds_read_b64_tr_b16 v[218:219], v185 offset:53760
	s_waitcnt lgkmcnt(7)
	v_mfma_f32_32x32x16_bf16 v[2:17], v[74:77], v[166:169], v[2:17]
	ds_read_b64_tr_b16 v[220:221], v185 offset:57344
	ds_read_b64_tr_b16 v[222:223], v185 offset:57856
	s_waitcnt lgkmcnt(8)
	v_mfma_f32_32x32x16_bf16 v[18:33], v[78:81], v[166:169], v[18:33]
	ds_read_b64_tr_b16 v[224:225], v185 offset:54272
	ds_read_b64_tr_b16 v[226:227], v185 offset:54784
	s_waitcnt lgkmcnt(9)
	v_mfma_f32_32x32x16_bf16 v[2:17], v[212:215], v[170:173], v[2:17]
	ds_read_b64_tr_b16 v[228:229], v185 offset:58368
	ds_read_b64_tr_b16 v[230:231], v185 offset:58880
	s_waitcnt lgkmcnt(10)
	v_mfma_f32_32x32x16_bf16 v[18:33], v[240:243], v[170:173], v[18:33]
	ds_read_b64_tr_b16 v[232:233], v185 offset:55296
	ds_read_b64_tr_b16 v[234:235], v185 offset:55808
	s_waitcnt lgkmcnt(11)
	v_mfma_f32_32x32x16_bf16 v[2:17], v[244:247], v[174:177], v[2:17]
	ds_read_b64_tr_b16 v[236:237], v185 offset:59392
	ds_read_b64_tr_b16 v[238:239], v185 offset:59904
	s_waitcnt lgkmcnt(12)
	v_mfma_f32_32x32x16_bf16 v[18:33], v[248:251], v[174:177], v[18:33]
	v_exp_f32_e32 v114, v114
	v_exp_f32_e32 v115, v115
	v_exp_f32_e32 v116, v116
	v_exp_f32_e32 v117, v117
	v_exp_f32_e32 v118, v118
	v_exp_f32_e32 v119, v119
	v_exp_f32_e32 v120, v120
	v_exp_f32_e32 v121, v121
	v_cvt_pk_bf16_f32 v66, v114, v115
	v_cvt_pk_bf16_f32 v67, v116, v117
	v_cvt_pk_bf16_f32 v68, v118, v119
	v_cvt_pk_bf16_f32 v69, v120, v121
	v_add_f32_e32 v178, v114, v115
	v_add_f32_e32 v179, v116, v117
	v_add_f32_e32 v180, v118, v119
	v_add_f32_e32 v181, v120, v121
	v_add_f32_e32 v178, v178, v179
	v_add_f32_e32 v180, v180, v181
	v_add_f32_e32 v178, v178, v180
	v_add_f32_e32 v210, v210, v178
	ds_read_b64_tr_b16 v[240:241], v185 offset:56320
	ds_read_b64_tr_b16 v[242:243], v185 offset:56832
	ds_read_b64_tr_b16 v[244:245], v185 offset:60416
	s_waitcnt lgkmcnt(11)
	ds_read_b64_tr_b16 v[246:247], v185 offset:60928
	ds_read_b64_tr_b16 v[114:115], v184 offset:53248
	ds_read_b64_tr_b16 v[116:117], v184 offset:53760
	ds_read_b64_tr_b16 v[118:119], v184 offset:57344
	s_waitcnt lgkmcnt(11)
	ds_read_b64_tr_b16 v[120:121], v184 offset:57856
	v_exp_f32_e32 v122, v122
	v_exp_f32_e32 v123, v123
	v_exp_f32_e32 v124, v124
	v_mfma_f32_32x32x16_bf16 v[34:49], v[66:69], v[216:219], v[34:49]
	v_exp_f32_e32 v125, v125
	v_exp_f32_e32 v126, v126
	v_exp_f32_e32 v127, v127
	v_exp_f32_e32 v128, v128
	v_exp_f32_e32 v129, v129
	v_cvt_pk_bf16_f32 v70, v122, v123
	v_cvt_pk_bf16_f32 v71, v124, v125
	v_mfma_f32_32x32x16_bf16 v[50:65], v[66:69], v[220:223], v[50:65]
	v_cvt_pk_bf16_f32 v72, v126, v127
	v_cvt_pk_bf16_f32 v73, v128, v129
	v_add_f32_e32 v178, v122, v123
	v_add_f32_e32 v179, v124, v125
	v_add_f32_e32 v180, v126, v127
	v_add_f32_e32 v181, v128, v129
	v_add_f32_e32 v178, v178, v179
	v_add_f32_e32 v180, v180, v181
	v_add_f32_e32 v178, v178, v180
	v_add_f32_e32 v210, v210, v178
	ds_read_b64_tr_b16 v[122:123], v184 offset:54272
	ds_read_b64_tr_b16 v[124:125], v184 offset:54784
	ds_read_b64_tr_b16 v[126:127], v184 offset:58368
	s_waitcnt lgkmcnt(11)
	ds_read_b64_tr_b16 v[128:129], v184 offset:58880
	v_exp_f32_e32 v98, v98
	v_exp_f32_e32 v99, v99
	v_exp_f32_e32 v100, v100
	v_mfma_f32_32x32x16_bf16 v[34:49], v[70:73], v[224:227], v[34:49]
	v_exp_f32_e32 v101, v101
	v_exp_f32_e32 v102, v102
	v_exp_f32_e32 v103, v103
	v_exp_f32_e32 v104, v104
	v_exp_f32_e32 v105, v105
	v_cvt_pk_bf16_f32 v74, v98, v99
	v_cvt_pk_bf16_f32 v75, v100, v101
	v_mfma_f32_32x32x16_bf16 v[50:65], v[70:73], v[228:231], v[50:65]
	v_cvt_pk_bf16_f32 v76, v102, v103
	v_cvt_pk_bf16_f32 v77, v104, v105
	v_add_f32_e32 v178, v98, v99
	v_add_f32_e32 v179, v100, v101
	v_add_f32_e32 v180, v102, v103
	v_add_f32_e32 v181, v104, v105
	v_add_f32_e32 v178, v178, v179
	v_add_f32_e32 v180, v180, v181
	v_add_f32_e32 v178, v178, v180
	v_add_f32_e32 v210, v210, v178
	ds_read_b64_tr_b16 v[98:99], v184 offset:55296
	ds_read_b64_tr_b16 v[100:101], v184 offset:55808
	ds_read_b64_tr_b16 v[102:103], v184 offset:59392
	s_waitcnt lgkmcnt(11)
	ds_read_b64_tr_b16 v[104:105], v184 offset:59904
	v_exp_f32_e32 v106, v106
	v_exp_f32_e32 v107, v107
	v_exp_f32_e32 v108, v108
	v_mfma_f32_32x32x16_bf16 v[34:49], v[74:77], v[232:235], v[34:49]
	v_exp_f32_e32 v109, v109
	v_exp_f32_e32 v110, v110
	v_exp_f32_e32 v111, v111
	v_exp_f32_e32 v112, v112
	v_exp_f32_e32 v113, v113
	v_cvt_pk_bf16_f32 v78, v106, v107
	v_cvt_pk_bf16_f32 v79, v108, v109
	v_mfma_f32_32x32x16_bf16 v[50:65], v[74:77], v[236:239], v[50:65]
	v_cvt_pk_bf16_f32 v80, v110, v111
	v_cvt_pk_bf16_f32 v81, v112, v113
	v_add_f32_e32 v178, v106, v107
	v_add_f32_e32 v179, v108, v109
	v_add_f32_e32 v180, v110, v111
	v_add_f32_e32 v181, v112, v113
	v_add_f32_e32 v178, v178, v179
	v_add_f32_e32 v180, v180, v181
	v_add_f32_e32 v178, v178, v180
	v_add_f32_e32 v210, v210, v178
	ds_read_b64_tr_b16 v[106:107], v184 offset:56320
	ds_read_b64_tr_b16 v[108:109], v184 offset:56832
	ds_read_b64_tr_b16 v[110:111], v184 offset:60416
	s_waitcnt lgkmcnt(11)
	ds_read_b64_tr_b16 v[112:113], v184 offset:60928
	v_exp_f32_e32 v2, v2
	v_exp_f32_e32 v3, v3
	v_exp_f32_e32 v4, v4
	v_mfma_f32_32x32x16_bf16 v[34:49], v[78:81], v[240:243], v[34:49]
	v_exp_f32_e32 v5, v5
	v_exp_f32_e32 v6, v6
	v_exp_f32_e32 v7, v7
	v_exp_f32_e32 v8, v8
	v_exp_f32_e32 v9, v9
	v_cvt_pk_bf16_f32 v66, v2, v3
	v_cvt_pk_bf16_f32 v67, v4, v5
	v_mfma_f32_32x32x16_bf16 v[50:65], v[78:81], v[244:247], v[50:65]
	v_cvt_pk_bf16_f32 v68, v6, v7
	v_cvt_pk_bf16_f32 v69, v8, v9
	v_add_f32_e32 v178, v2, v3
	v_add_f32_e32 v179, v4, v5
	v_add_f32_e32 v180, v6, v7
	v_add_f32_e32 v181, v8, v9
	v_add_f32_e32 v178, v178, v179
	v_add_f32_e32 v180, v180, v181
	v_add_f32_e32 v178, v178, v180
	v_add_f32_e32 v210, v210, v178
	v_exp_f32_e32 v10, v10
	v_exp_f32_e32 v11, v11
	v_exp_f32_e32 v12, v12
	v_mfma_f32_32x32x16_bf16 v[34:49], v[66:69], v[114:117], v[34:49]
	v_exp_f32_e32 v13, v13
	v_exp_f32_e32 v14, v14
	v_exp_f32_e32 v15, v15
	v_exp_f32_e32 v16, v16
	v_exp_f32_e32 v17, v17
	v_cvt_pk_bf16_f32 v70, v10, v11
	v_cvt_pk_bf16_f32 v71, v12, v13
	v_mfma_f32_32x32x16_bf16 v[50:65], v[66:69], v[118:121], v[50:65]
	v_cvt_pk_bf16_f32 v72, v14, v15
	v_cvt_pk_bf16_f32 v73, v16, v17
	v_add_f32_e32 v178, v10, v11
	v_add_f32_e32 v179, v12, v13
	v_add_f32_e32 v180, v14, v15
	v_add_f32_e32 v181, v16, v17
	v_add_f32_e32 v178, v178, v179
	v_add_f32_e32 v180, v180, v181
	v_add_f32_e32 v178, v178, v180
	v_add_f32_e32 v210, v210, v178
	v_exp_f32_e32 v18, v18
	v_exp_f32_e32 v19, v19
	v_exp_f32_e32 v20, v20
	s_waitcnt lgkmcnt(10)
	v_mfma_f32_32x32x16_bf16 v[34:49], v[70:73], v[122:125], v[34:49]
	v_exp_f32_e32 v21, v21
	v_exp_f32_e32 v22, v22
	v_exp_f32_e32 v23, v23
	v_exp_f32_e32 v24, v24
	v_exp_f32_e32 v25, v25
	v_cvt_pk_bf16_f32 v74, v18, v19
	v_cvt_pk_bf16_f32 v75, v20, v21
	s_waitcnt lgkmcnt(8)
	v_mfma_f32_32x32x16_bf16 v[50:65], v[70:73], v[126:129], v[50:65]
	v_cvt_pk_bf16_f32 v76, v22, v23
	v_cvt_pk_bf16_f32 v77, v24, v25
	v_add_f32_e32 v178, v18, v19
	v_add_f32_e32 v179, v20, v21
	v_add_f32_e32 v180, v22, v23
	v_add_f32_e32 v181, v24, v25
	v_add_f32_e32 v178, v178, v179
	v_add_f32_e32 v180, v180, v181
	v_add_f32_e32 v178, v178, v180
	v_add_f32_e32 v210, v210, v178
	v_exp_f32_e32 v26, v26
	v_exp_f32_e32 v27, v27
	v_exp_f32_e32 v28, v28
	s_waitcnt lgkmcnt(6)
	v_mfma_f32_32x32x16_bf16 v[34:49], v[74:77], v[98:101], v[34:49]
	v_exp_f32_e32 v29, v29
	v_exp_f32_e32 v30, v30
	v_exp_f32_e32 v31, v31
	v_exp_f32_e32 v32, v32
	v_exp_f32_e32 v33, v33
	v_cvt_pk_bf16_f32 v78, v26, v27
	v_cvt_pk_bf16_f32 v79, v28, v29
	s_waitcnt lgkmcnt(4)
	v_mfma_f32_32x32x16_bf16 v[50:65], v[74:77], v[102:105], v[50:65]
	v_cvt_pk_bf16_f32 v80, v30, v31
	v_cvt_pk_bf16_f32 v81, v32, v33
	v_add_f32_e32 v178, v26, v27
	v_add_f32_e32 v179, v28, v29
	v_add_f32_e32 v180, v30, v31
	v_add_f32_e32 v181, v32, v33
	v_add_f32_e32 v178, v178, v179
	v_add_f32_e32 v180, v180, v181
	v_add_f32_e32 v178, v178, v180
	v_add_f32_e32 v210, v210, v178
	s_waitcnt lgkmcnt(2)
	v_mfma_f32_32x32x16_bf16 v[34:49], v[78:81], v[106:109], v[34:49]
	s_waitcnt lgkmcnt(0)
	v_mfma_f32_32x32x16_bf16 v[50:65], v[78:81], v[110:113], v[50:65]
	v_cmp_lt_f32_e32 vcc, 0x4b800000, v210
	s_cbranch_vccnz .Latt_rs
